# k48 + waves 1-4 touch the next phase's first weight tile (first two K-tiles) while the workgroup waits at each of the four GEMM-phase seams
# baseline (speedup 1.0000x reference)
.LBB0_594:
	s_waitcnt vmcnt(0)
	s_sub_i32 s98, s93, 1
	s_cmp_lt_u32 s98, 4
	s_cbranch_scc0 .Lwpf4_skip
	v_mbcnt_lo_u32_b32 v249, -1, 0
	v_mbcnt_hi_u32_b32 v249, -1, v249
	s_lshl_b32 s98, s98, 6
	v_add_u32_e32 v249, s98, v249
	v_lshlrev_b32_e32 v249, 11, v249
	s_lshr_b32 s98, s2, 6
	s_lshl_b32 s98, s98, 19
	s_add_u32 s98, s98, 0x600000
	s_add_u32 s98, s0, s98
	s_addc_u32 s99, s1, 0
	global_load_dword v252, v249, s[98:99]
	global_load_dword v253, v249, s[98:99] offset:128
.Lwpf4_skip:
	v_readlane_b32 s6, v248, 5
	v_readlane_b32 s7, v248, 6
	s_and_b64 vcc, exec, s[6:7]
	s_barrier
	s_cbranch_vccz .LBB0_648
	v_mbcnt_lo_u32_b32 v0, -1, 0
	v_mbcnt_hi_u32_b32 v0, -1, v0
	s_nop 0
	v_cmp_eq_u32_e32 vcc, 0, v0
	s_and_saveexec_b64 s[6:7], vcc
	s_cbranch_execz .LBB0_647
	s_add_i32 s8, 0, 0x20160
	v_mov_b32_e32 v0, s8
	s_waitcnt vmcnt(0) expcnt(0) lgkmcnt(0)
	ds_read_b32 v2, v0
	s_add_i32 s8, 0, 0x20164
	v_mov_b32_e32 v0, s8
	ds_read_b32 v0, v0
	s_waitcnt lgkmcnt(1)
	v_cmp_ne_u32_e32 vcc, 0, v2
	s_cbranch_vccnz .LBB0_611
	v_readlane_b32 s8, v248, 0
	v_readlane_b32 s9, v248, 1
	s_load_dwordx2 s[12:13], s[8:9], 0x4
	s_add_u32 s8, s0, 0x4200
	s_addc_u32 s9, s1, 0
	s_add_u32 s10, s0, 0x4400
	s_addc_u32 s11, s1, 0
	s_waitcnt lgkmcnt(0)
	s_mul_i32 s14, s12, s33
	s_add_u32 s12, s0, 0x4500
	s_mul_i32 s14, s14, s13
	s_addc_u32 s13, s1, 0
	s_add_u32 s16, s0, 0x4600
	s_addc_u32 s17, s1, 0
	s_add_u32 s18, s0, 0x4700
	s_addc_u32 s19, s1, 0
	s_add_u32 s20, s0, 0x4800
	s_addc_u32 s21, s1, 0
	s_add_u32 s22, s0, 0x4900
	s_addc_u32 s23, s1, 0
	s_add_u32 s40, s0, 0x4a00
	s_addc_u32 s41, s1, 0
	s_add_u32 s42, s0, 0x4b00
	s_addc_u32 s43, s1, 0
	s_add_u32 s44, s0, 0x4c00
	s_addc_u32 s45, s1, 0
	s_add_u32 s46, s0, 0x4d00
	s_addc_u32 s47, s1, 0
	s_add_u32 s48, s0, 0x4e00
	s_addc_u32 s49, s1, 0
	s_add_u32 s50, s0, 0x4f00
	s_addc_u32 s51, s1, 0
	s_add_u32 s52, s0, 0x5000
	s_addc_u32 s53, s1, 0
	s_add_u32 s54, s0, 0x5100
	s_addc_u32 s55, s1, 0
	s_add_u32 s56, s0, 0x5200
	s_addc_u32 s57, s1, 0
	s_add_u32 s58, s0, 0x5300
	s_addc_u32 s59, s1, 0
	s_mov_b32 s15, 1
	v_mov_b32_e32 v16, 0
	s_branch .LBB0_599

.LBB0_648:
	s_mov_b64 s[46:47], s[96:97]
	s_waitcnt vmcnt(0) lgkmcnt(0)
	s_barrier
	s_load_dwordx4 s[16:19], s[46:47], 0xd8
	s_add_u32 s42, s0, 0x28000
	s_addc_u32 s43, s1, 0
	s_lshl_b32 s35, s2, 3
	s_add_i32 s40, s93, s35
	s_cmp_lt_i32 s2, 64
	s_cbranch_scc0 .LBB0_662
	v_mbcnt_lo_u32_b32 v0, -1, 0
	v_mbcnt_hi_u32_b32 v0, -1, v0
	s_cmpk_gt_i32 s40, 0x1ff
	v_add_u32_e32 v0, s73, v0
	s_load_dwordx8 s[8:15], s[46:47], 0x50
	s_load_dwordx2 s[6:7], s[46:47], 0x70
	v_and_b32_e32 v5, 63, v0
	v_lshlrev_b32_e32 v0, 2, v5
	s_waitcnt lgkmcnt(0)
	global_load_dword v87, v0, s[8:9]
	global_load_dword v88, v0, s[10:11]
	global_load_dword v89, v0, s[12:13]
	global_load_dword v90, v0, s[14:15]
	s_cbranch_scc1 .LBB0_657
	v_lshlrev_b32_e32 v10, 3, v5
	s_waitcnt lgkmcnt(0)
	global_load_dwordx2 v[2:3], v10, s[6:7]
	s_add_u32 s14, s18, 0x29300000
	s_addc_u32 s15, s19, 0
	s_add_u32 s24, s18, 0x29400000
	v_mov_b32_e32 v1, 0
	s_addc_u32 s25, s19, 0
	s_add_u32 s26, s18, 0x8000000
	v_lshl_add_u64 v[6:7], s[16:17], 0, v[0:1]
	s_mov_b64 s[6:7], 0x80f8000
	v_mov_b32_e32 v11, v1
	s_addc_u32 s27, s19, 0
	v_lshl_add_u64 v[6:7], v[6:7], 0, s[6:7]
	v_lshl_add_u64 v[10:11], s[16:17], 0, v[10:11]
	s_mov_b64 s[6:7], 0x8138000
	s_bfe_u32 s28, s75, 0x20006
	v_lshl_add_u64 v[10:11], v[10:11], 0, s[6:7]
	s_sub_i32 s6, 0, s28
	s_cmp_eq_u32 s28, 0
	v_cvt_f32_i32_e32 v9, s6
	s_cselect_b64 s[6:7], -1, 0
	s_sub_i32 s8, 1, s28
	s_cmp_lt_u32 s28, 2
	v_cvt_f32_i32_e32 v23, s8
	s_cselect_b64 s[8:9], -1, 0
	s_sub_i32 s10, 2, s28
	v_cvt_f32_i32_e32 v28, s10
	s_cmp_eq_u32 s28, 3
	v_lshlrev_b32_e32 v8, 1, v5
	s_cselect_b64 s[10:11], -1, 0
	s_xor_b32 s12, s28, 3
	s_mov_b32 s21, 0
	v_cvt_f32_ubyte0_e32 v29, s12
	s_or_b32 s29, s28, 4
	v_mov_b32_e32 v30, 0xff800000
	v_lshlrev_b32_e32 v31, 2, v8
	v_mov_b32_e32 v32, 0x358637bd
	s_mov_b32 s30, 0xf800000
	v_mov_b32_e32 v33, 0x260
	s_mov_b32 s31, 0x3f4ccccd
	s_movk_i32 s41, 0x7fff
	s_mov_b32 s72, 0xffff0000
	v_mov_b32_e32 v34, 0x3bb8aa3b
	v_mov_b32_e32 v35, 0x3cb8aa3b
	v_mov_b32_e32 v36, 1
	s_mov_b32 s75, s40
	s_branch .LBB0_652

.LBB0_775:
	s_waitcnt vmcnt(0)
	s_sub_i32 s98, s93, 1
	s_cmp_lt_u32 s98, 4
	s_cbranch_scc0 .Lwpf6_skip
	v_mbcnt_lo_u32_b32 v249, -1, 0
	v_mbcnt_hi_u32_b32 v249, -1, v249
	s_lshl_b32 s98, s98, 6
	v_add_u32_e32 v249, s98, v249
	v_lshlrev_b32_e32 v249, 11, v249
	s_lshr_b32 s98, s2, 6
	s_lshl_b32 s98, s98, 19
	s_add_u32 s98, s98, 0x800000
	s_add_u32 s98, s0, s98
	s_addc_u32 s99, s1, 0
	global_load_dword v252, v249, s[98:99]
	global_load_dword v253, v249, s[98:99] offset:128
.Lwpf6_skip:
	s_and_b64 vcc, exec, s[94:95]
	s_barrier
	s_cbranch_vccnz .LBB0_829
	v_mbcnt_lo_u32_b32 v0, -1, 0
	v_mbcnt_hi_u32_b32 v0, -1, v0
	s_nop 0
	v_cmp_eq_u32_e32 vcc, 0, v0
	s_and_saveexec_b64 s[8:9], vcc
	s_cbranch_execz .LBB0_828
	s_and_b32 s10, s2, 7
	s_lshl_b32 s10, s10, 3
	s_bfe_u32 s11, s2, 0x30003
	s_or_b32 s10, s10, s11
	s_lshl_b32 s10, s10, 8
	s_add_u32 s12, s0, 0x14000
	s_addc_u32 s13, s1, 0
	s_add_u32 s12, s12, s10
	s_addc_u32 s13, s13, 0
	s_add_u32 s14, s0, 0x28500
	s_addc_u32 s15, s1, 0
	v_mov_b32_e32 v0, 0
	v_mov_b32_e32 v1, 1
	s_waitcnt vmcnt(0) lgkmcnt(0)
	global_atomic_add v0, v1, s[12:13]
	global_atomic_add v0, v1, s[14:15]
	s_mov_b32 s16, 0

.LBB0_829:
	s_mov_b64 s[10:11], s[96:97]
	s_waitcnt vmcnt(0) lgkmcnt(0)
	s_barrier
	s_load_dwordx2 s[12:13], s[10:11], 0xe0
	s_add_i32 s66, s93, 0x4000
	s_add_u32 s22, s0, 0x28100
	s_addc_u32 s23, s1, 0
	s_cmp_lt_i32 s2, 16
	s_cbranch_scc0 .LBB0_838
	s_add_i32 s42, s35, s66
	v_mbcnt_lo_u32_b32 v0, -1, 0
	v_mbcnt_hi_u32_b32 v0, -1, v0
	s_cmpk_gt_i32 s42, 0x407f
	v_add_u32_e32 v0, s73, v0
	s_cbranch_scc1 .LBB0_833
	s_load_dwordx4 s[24:27], s[10:11], 0xa0
	s_load_dwordx4 s[16:19], s[10:11], 0x0
	v_and_b32_e32 v0, 63, v0
	s_ashr_i32 s41, s40, 31
	v_lshlrev_b32_e32 v2, 4, v0
	s_lshl_b64 s[8:9], s[40:41], 12
	s_ashr_i32 s43, s42, 31
	v_or_b32_e32 v12, s8, v2
	v_mov_b32_e32 v13, s9
	s_lshl_b64 s[8:9], s[42:43], 11
	v_mov_b32_e32 v3, 0
	s_ashr_i32 s35, s34, 31
	v_lshl_or_b32 v14, v0, 3, s8
	v_mov_b32_e32 v15, s9
	s_lshl_b64 s[8:9], s[42:43], 12
	s_waitcnt lgkmcnt(0)
	v_lshl_add_u64 v[8:9], s[24:25], 0, v[2:3]
	v_lshl_add_u64 v[10:11], s[26:27], 0, v[2:3]
	s_lshl_b64 s[44:45], s[34:35], 12
	s_lshl_b64 s[46:47], s[34:35], 11
	v_or_b32_e32 v16, s8, v2
	v_mov_b32_e32 v17, s9
	s_mov_b32 s14, 0x29900000
	s_mov_b32 s15, 0x29980000
	s_mov_b32 s24, 0x29a00000
	s_mov_b32 s25, 0x29a80000
	v_lshlrev_b32_e32 v22, 4, v0
	v_mov_b32_e32 v23, 0x358637bd
	s_mov_b32 s26, 0xf800000
	v_mov_b32_e32 v24, 0x260
	s_mov_b32 s27, 0xe200000
	s_movk_i32 s28, 0x7fff
	s_mov_b32 s29, 0xffff0000
	s_mov_b32 s30, 0x12300000

.LBB0_883:
	s_waitcnt vmcnt(0)
	s_sub_i32 s98, s93, 1
	s_cmp_lt_u32 s98, 4
	s_cbranch_scc0 .Lwpf8_skip
	v_mbcnt_lo_u32_b32 v249, -1, 0
	v_mbcnt_hi_u32_b32 v249, -1, v249
	s_lshl_b32 s98, s98, 6
	v_add_u32_e32 v249, s98, v249
	v_lshlrev_b32_e32 v249, 13, v249
	s_lshr_b32 s98, s2, 6
	s_lshl_b32 s98, s98, 21
	s_add_u32 s98, s98, 0x1000000
	s_add_u32 s98, s0, s98
	s_addc_u32 s99, s1, 0
	global_load_dword v252, v249, s[98:99]
	global_load_dword v253, v249, s[98:99] offset:128
.Lwpf8_skip:
	s_and_b64 vcc, exec, s[94:95]
	s_barrier
	s_cbranch_vccnz .LBB0_937
	v_mbcnt_lo_u32_b32 v0, -1, 0
	v_mbcnt_hi_u32_b32 v0, -1, v0
	s_nop 0
	v_cmp_eq_u32_e32 vcc, 0, v0
	s_and_saveexec_b64 s[8:9], vcc
	s_cbranch_execz .LBB0_936
	s_add_i32 s10, 0, 0x20160
	v_mov_b32_e32 v0, s10
	s_waitcnt vmcnt(0) expcnt(0) lgkmcnt(0)
	ds_read_b32 v2, v0
	s_add_i32 s10, 0, 0x20164
	v_mov_b32_e32 v0, s10
	ds_read_b32 v0, v0
	s_waitcnt lgkmcnt(1)
	v_cmp_ne_u32_e32 vcc, 0, v2
	s_cbranch_vccnz .LBB0_900
	v_readlane_b32 s10, v248, 0
	v_readlane_b32 s11, v248, 1
	s_load_dwordx2 s[14:15], s[10:11], 0x4
	s_add_u32 s10, s0, 0x4400
	s_addc_u32 s11, s1, 0
	s_add_u32 s12, s0, 0x4500
	s_addc_u32 s13, s1, 0
	s_add_u32 s16, s0, 0x4600
	s_addc_u32 s17, s1, 0
	s_add_u32 s18, s0, 0x4700
	s_addc_u32 s19, s1, 0
	s_add_u32 s22, s0, 0x4800
	s_addc_u32 s23, s1, 0
	s_add_u32 s34, s0, 0x4900
	s_addc_u32 s35, s1, 0
	s_add_u32 s40, s0, 0x4a00
	s_addc_u32 s41, s1, 0
	s_add_u32 s42, s0, 0x4b00
	s_addc_u32 s43, s1, 0
	s_add_u32 s44, s0, 0x4c00
	s_addc_u32 s45, s1, 0
	s_add_u32 s46, s0, 0x4d00
	s_addc_u32 s47, s1, 0
	s_add_u32 s48, s0, 0x4e00
	s_addc_u32 s49, s1, 0
	s_add_u32 s50, s0, 0x4f00
	s_addc_u32 s51, s1, 0
	s_add_u32 s52, s0, 0x5000
	s_addc_u32 s53, s1, 0
	s_add_u32 s54, s0, 0x5100
	s_addc_u32 s55, s1, 0
	s_add_u32 s56, s0, 0x5200
	s_addc_u32 s57, s1, 0
	s_waitcnt lgkmcnt(0)
	s_mul_i32 s14, s14, s33
	s_add_u32 s58, s0, 0x5300
	s_mul_i32 s14, s14, s15
	s_addc_u32 s59, s1, 0
	s_mov_b32 s15, 1
	v_mov_b32_e32 v16, 0
	s_branch .LBB0_888

.LBB0_937:
	s_mov_b64 s[10:11], s[96:97]
	s_waitcnt vmcnt(0) lgkmcnt(0)
	s_barrier
	s_load_dwordx2 s[18:19], s[10:11], 0xe0
	s_and_b64 vcc, exec, s[38:39]
	s_cbranch_vccz .LBB0_939
	s_and_b64 s[8:9], s[36:37], exec
	s_cselect_b32 s8, s79, s78
	v_readlane_b32 s9, v248, 7
	s_add_i32 s8, s8, s9
	s_ashr_i32 s9, s8, 31
	s_lshr_b32 s9, s9, 27
	s_add_i32 s9, s8, s9
	s_ashr_i32 s12, s9, 5
	s_sub_i32 s12, 0, s12
	s_lshl_b32 s12, s12, 3
	s_min_i32 s12, s12, 0xffffffc8
	s_add_i32 s13, s12, 64
	s_sub_i32 s12, 0xffffffc0, s12
	s_max_i32 s12, s13, s12
	v_cvt_f32_u32_e32 v0, s12
	s_sub_i32 s13, 0, s12
	s_andn2_b32 s9, s9, 31
	s_sub_i32 s8, s8, s9
	v_rcp_iflag_f32_e32 v0, v0
	s_ashr_i32 s9, s8, 31
	s_abs_i32 s8, s8
	v_mul_f32_e32 v0, 0x4f7ffffe, v0
	v_cvt_u32_f32_e32 v0, v0
	s_nop 0
	v_readfirstlane_b32 s14, v0
	s_mul_i32 s13, s13, s14
	s_mul_hi_u32 s13, s14, s13
	s_add_i32 s14, s14, s13
	s_mul_hi_u32 s13, s8, s14
	s_mul_i32 s13, s13, s12
	s_sub_i32 s8, s8, s13
	s_sub_i32 s13, s8, s12
	s_cmp_ge_u32 s8, s12
	s_cselect_b32 s8, s13, s8
	s_sub_i32 s13, s8, s12
	s_cmp_ge_u32 s8, s12
	s_cselect_b32 s8, s13, s8
	s_xor_b32 s8, s8, s9
	s_sub_i32 s8, s8, s9
	s_bitcmp1_b32 s8, 0
	s_cselect_b64 s[12:13], -1, 0

.LBB0_1005:
	s_waitcnt vmcnt(0)
	s_sub_i32 s98, s93, 1
	s_cmp_lt_u32 s98, 4
	s_cbranch_scc0 .Lwpf9_skip
	v_mbcnt_lo_u32_b32 v249, -1, 0
	v_mbcnt_hi_u32_b32 v249, -1, v249
	s_lshl_b32 s98, s98, 6
	v_add_u32_e32 v249, s98, v249
	v_lshlrev_b32_e32 v249, 11, v249
	s_lshr_b32 s98, s2, 6
	s_lshl_b32 s98, s98, 19
	s_add_u32 s98, s98, 0x1800000
	s_add_u32 s98, s0, s98
	s_addc_u32 s99, s1, 0
	global_load_dword v252, v249, s[98:99]
	global_load_dword v253, v249, s[98:99] offset:128
.Lwpf9_skip:
	v_readlane_b32 s4, v248, 5
	v_readlane_b32 s5, v248, 6
	s_and_b64 vcc, exec, s[4:5]
	s_barrier
	s_cbranch_vccz .LBB0_1059
	v_mbcnt_lo_u32_b32 v0, -1, 0
	v_mbcnt_hi_u32_b32 v0, -1, v0
	s_nop 0
	v_cmp_eq_u32_e32 vcc, 0, v0
	s_and_saveexec_b64 s[4:5], vcc
	s_cbranch_execz .LBB0_1058
	s_and_b32 s10, s2, 7
	s_lshl_b32 s10, s10, 3
	s_bfe_u32 s11, s2, 0x30003
	s_or_b32 s10, s10, s11
	s_lshl_b32 s10, s10, 8
	s_add_u32 s12, s0, 0x29000
	s_addc_u32 s13, s1, 0
	s_add_u32 s12, s12, s10
	s_addc_u32 s13, s13, 0
	s_add_u32 s14, s0, 0x28400
	s_addc_u32 s15, s1, 0
	v_mov_b32_e32 v0, 0
	v_mov_b32_e32 v1, 1
	s_waitcnt vmcnt(0) lgkmcnt(0)
	global_atomic_add v0, v1, s[12:13]
	global_atomic_add v0, v1, s[14:15]
	s_mov_b32 s16, 0

.LBB0_1059:
	s_waitcnt vmcnt(0) lgkmcnt(0)
	s_barrier
	s_load_dwordx4 s[8:11], s[96:97], 0xd8
	s_add_u32 s12, s0, 0x28200
	s_addc_u32 s13, s1, 0
	s_add_i32 s0, s33, 13
	s_ashr_i32 s14, s0, 4
	s_and_b32 s0, s92, 15
	s_cmp_eq_u32 s0, 2
	s_cbranch_scc0 .LBB0_1068
	s_ashr_i32 s0, s92, 1
	s_and_b32 s0, s0, -8
	s_add_i32 s16, s66, s0
	v_mbcnt_lo_u32_b32 v0, -1, 0
	v_mbcnt_hi_u32_b32 v0, -1, v0
	s_cmpk_gt_i32 s16, 0x407f
	v_add_u32_e32 v0, s73, v0
	s_cbranch_scc1 .LBB0_1063
	s_load_dwordx2 s[4:5], s[96:97], 0xb0
	v_and_b32_e32 v2, 63, v0
	v_mov_b32_e32 v7, 0
	v_lshlrev_b32_e32 v6, 4, v2
	s_ashr_i32 s17, s16, 31
	s_add_i32 s0, s93, s0
	s_lshl_b32 s18, s14, 3
	s_waitcnt lgkmcnt(0)
	v_lshl_add_u64 v[0:1], s[4:5], 0, v[6:7]
	s_lshl_b64 s[4:5], s[16:17], 11
	s_ashr_i32 s1, s0, 31
	v_lshl_or_b32 v2, v2, 3, s4
	v_mov_b32_e32 v3, s5
	s_ashr_i32 s19, s18, 31
	s_lshl_b64 s[4:5], s[16:17], 12
	s_lshl_b64 s[0:1], s[0:1], 12
	s_lshl_b64 s[22:23], s[18:19], 11
	v_or_b32_e32 v4, s4, v6
	v_mov_b32_e32 v5, s5
	s_lshl_b64 s[24:25], s[18:19], 12
	v_or_b32_e32 v6, s0, v6
	v_mov_b32_e32 v7, s1
	v_mov_b32_e32 v12, 0x358637bd
	s_mov_b32 s0, 0xf800000
	v_mov_b32_e32 v13, 0x260
	s_mov_b32 s1, 0xe200000
	s_mov_b32 s15, 0x20700000
	s_movk_i32 s17, 0x7fff
	s_mov_b32 s19, 0xffff0000
	s_mov_b32 s26, 0x24800000
